# unmasked tiles: scale/max VALU interleaved into S=KQ^T MFMA gaps (dependency-tracked reorder)
# baseline (speedup 1.0000x reference)
; template <int MODE> ...
;     ...
;     f32x4 S[2][2][2][2];
; #pragma unroll
;     for (int kh = 0; kh < 2; ++kh) {
;       bf16x8 kf[2][2];
; #pragma unroll
;       for (int t = 0; t < 2; ++t)
; #pragma unroll
;         for (int s2 = 0; s2 < 2; ++s2)
;           kf[t][s2] = *(const bf16x8*)&Ks[(kh * 32 + t * 16 + r) * 64 + (((s2 * 4 + g) ^ (r & 7)) * 8)];
; #pragma unroll
;       for (int tt = 0; tt < 2; ++tt)
; #pragma unroll
;         for (int hh = 0; hh < 2; ++hh) {
;           f32x4 s0 = zero4(), s1 = zero4();
;           if constexpr (MODE == 0) {
;             s0 = MFMA(kf[0][0], qf[tt][hh][0], s0);
;             s1 = MFMA(kf[1][0], qf[tt][hh][0], s1);
;             s0 = MFMA(kf[0][1], qf[tt][hh][1], s0);
;             s1 = MFMA(kf[1][1], qf[tt][hh][1], s1);
;           } else {
;             s0 = MFMA(kf[0][hh], qf[tt][hh][0], s0);
;             s1 = MFMA(kf[1][hh], qf[tt][hh][0], s1);
;           }
;           S[kh][tt][hh][0] = s0;
;           S[kh][tt][hh][1] = s1;
;         }
;     }
;     if (masked) {
; #pragma unroll
;       for (int kh = 0; kh < 2; ++kh)
; #pragma unroll
;         for (int tt = 0; tt < 2; ++tt) {
;           const int qpos = qtok0 + w * 32 + tt * 16 + r;
;           const int kp0 = kt0 + kh * 32 + g * 8;
; #pragma unroll
;           for (int t = 0; t < 2; ++t)
; #pragma unroll
;             for (int j = 0; j < 4; ++j) {
;               int d = kp0 + t * 4 + j - qpos;
;               d = d < 0 ? -d : d;
;               if (d > 128) { S[kh][tt][0][t][j] = -INFINITY; S[kh][tt][1][t][j] = -INFINITY; }
;             }
;         }
;     }
; #pragma unroll
;     for (int tt = 0; tt < 2; ++tt)
; #pragma unroll
;       for (int hh = 0; hh < 2; ++hh) {
;         const float nb = nbias[tt][hh];
; #pragma unroll
;         for (int kh = 0; kh < 2; ++kh)
; #pragma unroll
;           for (int t = 0; t < 2; ++t) S[kh][tt][hh][t] = S[kh][tt][hh][t] * c1 + nb;
;       }
;     {
;       float mxq[2][2];
;       bool need = first;
; #pragma unroll
;       for (int tt = 0; tt < 2; ++tt)
; #pragma unroll
;         for (int hh = 0; hh < 2; ++hh) {
;           const float m0 = fmaxf(fmaxf(S[0][tt][hh][0][0], S[0][tt][hh][0][1]), S[0][tt][hh][0][2]);
;           const float m1 = fmaxf(fmaxf(S[0][tt][hh][1][0], S[0][tt][hh][1][1]), S[0][tt][hh][1][2]);
;           const float m2 = fmaxf(fmaxf(S[1][tt][hh][0][0], S[1][tt][hh][0][1]), S[1][tt][hh][0][2]);
.LBB0_869:
	s_and_b64 vcc, exec, s[58:59]
	s_cbranch_vccnz .Lattn1_sorig
	s_add_i32 s60, s2, 0xffffe000
	s_and_b32 s60, s60, 0x2000
	v_lshl_add_u32 v0, s60, 1, v233
	v_add_u32_e32 v234, v0, v230
	v_add_u32_e32 v0, v0, v231
	ds_read_b128 v[108:111], v234
	ds_read_b128 v[112:115], v234 offset:2048
	ds_read_b128 v[120:123], v0
	ds_read_b128 v[132:135], v0 offset:2048
	s_waitcnt lgkmcnt(3)
	v_mfma_f32_16x16x32_bf16 v[116:119], v[108:111], v[68:71], 0
	ds_read_b128 v[190:193], v0 offset:4096
	ds_read_b128 v[196:199], v0 offset:6144
	s_andn2_b64 vcc, exec, s[58:59]
	s_waitcnt lgkmcnt(4)
	v_mfma_f32_16x16x32_bf16 v[124:127], v[112:115], v[68:71], 0
	s_waitcnt lgkmcnt(3)
	v_mfma_f32_16x16x32_bf16 v[160:163], v[120:123], v[72:75], v[116:119]
	v_mfma_f32_16x16x32_bf16 v[116:119], v[108:111], v[76:79], 0
	s_waitcnt lgkmcnt(2)
	v_mfma_f32_16x16x32_bf16 v[156:159], v[132:135], v[72:75], v[124:127]
	v_mfma_f32_16x16x32_bf16 v[124:127], v[112:115], v[76:79], 0
	v_mfma_f32_16x16x32_bf16 v[144:147], v[120:123], v[80:83], v[116:119]
	v_mfma_f32_16x16x32_bf16 v[116:119], v[108:111], v[84:87], 0
	v_mfma_f32_16x16x32_bf16 v[108:111], v[108:111], v[92:95], 0
	v_mfma_f32_16x16x32_bf16 v[140:143], v[132:135], v[80:83], v[124:127]
	v_mfma_f32_16x16x32_bf16 v[124:127], v[112:115], v[84:87], 0
	v_mfma_f32_16x16x32_bf16 v[128:131], v[120:123], v[88:91], v[116:119]
	v_mfma_f32_16x16x32_bf16 v[116:119], v[112:115], v[92:95], 0
	v_mfma_f32_16x16x32_bf16 v[112:115], v[120:123], v[96:99], v[108:111]
	ds_read_b128 v[120:123], v234 offset:4096
	v_mfma_f32_16x16x32_bf16 v[108:111], v[132:135], v[96:99], v[116:119]
	s_nop 4
	ds_read_b128 v[116:119], v234 offset:6144
	v_mfma_f32_16x16x32_bf16 v[124:127], v[132:135], v[88:91], v[124:127]
	v_pk_fma_f32 v[204:205], v[142:143], s[28:29], v[178:179] op_sel_hi:[1,0,0]
	s_waitcnt lgkmcnt(1)
	v_mfma_f32_16x16x32_bf16 v[132:135], v[120:123], v[68:71], 0
	v_pk_fma_f32 v[206:207], v[140:141], s[28:29], v[178:179] op_sel_hi:[1,0,0]
	s_waitcnt lgkmcnt(0)
	v_mfma_f32_16x16x32_bf16 v[136:139], v[116:119], v[68:71], 0
	v_pk_fma_f32 v[130:131], v[130:131], s[28:29], v[2:3] op_sel_hi:[1,0,0]
	v_mfma_f32_16x16x32_bf16 v[168:171], v[190:193], v[72:75], v[132:135]
	v_pk_fma_f32 v[126:127], v[126:127], s[28:29], v[2:3] op_sel_hi:[1,0,0]
	v_mfma_f32_16x16x32_bf16 v[132:135], v[120:123], v[76:79], 0
	v_pk_fma_f32 v[124:125], v[124:125], s[28:29], v[2:3] op_sel_hi:[1,0,0]
	v_mfma_f32_16x16x32_bf16 v[164:167], v[196:199], v[72:75], v[136:139]
	v_pk_fma_f32 v[128:129], v[128:129], s[28:29], v[2:3] op_sel_hi:[1,0,0]
	v_mfma_f32_16x16x32_bf16 v[136:139], v[116:119], v[76:79], 0
	v_mfma_f32_16x16x32_bf16 v[152:155], v[190:193], v[80:83], v[132:135]
	v_mfma_f32_16x16x32_bf16 v[132:135], v[120:123], v[84:87], 0
	v_pk_fma_f32 v[170:171], v[170:171], s[28:29], v[180:181] op_sel_hi:[1,0,0]
	v_mfma_f32_16x16x32_bf16 v[200:203], v[116:119], v[84:87], 0
	v_pk_fma_f32 v[168:169], v[168:169], s[28:29], v[180:181] op_sel_hi:[1,0,0]
	v_mfma_f32_16x16x32_bf16 v[120:123], v[120:123], v[92:95], 0
	v_pk_fma_f32 v[166:167], v[166:167], s[28:29], v[180:181] op_sel_hi:[1,0,0]
	v_mfma_f32_16x16x32_bf16 v[116:119], v[116:119], v[92:95], 0
	v_pk_fma_f32 v[164:165], v[164:165], s[28:29], v[180:181] op_sel_hi:[1,0,0]
	v_mfma_f32_16x16x32_bf16 v[148:151], v[196:199], v[80:83], v[136:139]
	v_pk_fma_f32 v[142:143], v[152:153], s[28:29], v[178:179] op_sel_hi:[1,0,0]
	v_mfma_f32_16x16x32_bf16 v[136:139], v[190:193], v[88:91], v[132:135]
	v_pk_fma_f32 v[140:141], v[154:155], s[28:29], v[178:179] op_sel_hi:[1,0,0]
	v_mfma_f32_16x16x32_bf16 v[132:135], v[196:199], v[88:91], v[200:203]
	v_mfma_f32_16x16x32_bf16 v[120:123], v[190:193], v[96:99], v[120:123]
	v_pk_fma_f32 v[190:191], v[162:163], s[28:29], v[180:181] op_sel_hi:[1,0,0]
	v_mfma_f32_16x16x32_bf16 v[116:119], v[196:199], v[96:99], v[116:119]
	v_pk_fma_f32 v[196:197], v[158:159], s[28:29], v[180:181] op_sel_hi:[1,0,0]
	v_pk_fma_f32 v[198:199], v[156:157], s[28:29], v[180:181] op_sel_hi:[1,0,0]
	v_pk_fma_f32 v[192:193], v[160:161], s[28:29], v[180:181] op_sel_hi:[1,0,0]
	v_pk_fma_f32 v[200:201], v[146:147], s[28:29], v[178:179] op_sel_hi:[1,0,0]
	v_pk_fma_f32 v[146:147], v[148:149], s[28:29], v[178:179] op_sel_hi:[1,0,0]
	v_pk_fma_f32 v[148:149], v[138:139], s[28:29], v[2:3] op_sel_hi:[1,0,0]
	v_pk_fma_f32 v[138:139], v[108:109], s[28:29], v[176:177] op_sel_hi:[1,0,0]
	v_max3_f32 v109, v198, v199, v196
	v_pk_fma_f32 v[152:153], v[134:135], s[28:29], v[2:3] op_sel_hi:[1,0,0]
	v_pk_fma_f32 v[134:135], v[112:113], s[28:29], v[176:177] op_sel_hi:[1,0,0]
	v_max3_f32 v108, v192, v193, v190
	v_max_f32_e32 v112, v191, v197
	v_max3_f32 v109, v171, v167, v109
	v_pk_fma_f32 v[202:203], v[144:145], s[28:29], v[178:179] op_sel_hi:[1,0,0]
	v_pk_fma_f32 v[144:145], v[150:151], s[28:29], v[178:179] op_sel_hi:[1,0,0]
	v_pk_fma_f32 v[150:151], v[136:137], s[28:29], v[2:3] op_sel_hi:[1,0,0]
	v_pk_fma_f32 v[136:137], v[110:111], s[28:29], v[176:177] op_sel_hi:[1,0,0]
	v_max3_f32 v110, v168, v169, v170
	v_max3_f32 v111, v164, v165, v166
	v_max3_f32 v108, v112, v108, v109
	v_max3_f32 v109, v206, v207, v204
	v_max3_f32 v111, v110, v111, v108
	v_max3_f32 v108, v202, v203, v200
	v_max_f32_e32 v113, v201, v205
	v_max3_f32 v109, v141, v145, v109
	v_max3_f32 v110, v142, v143, v140
	v_max3_f32 v112, v146, v147, v144
	v_max3_f32 v108, v113, v108, v109
	v_max3_f32 v109, v124, v125, v126
	v_pk_fma_f32 v[154:155], v[132:133], s[28:29], v[2:3] op_sel_hi:[1,0,0]
	v_pk_fma_f32 v[132:133], v[114:115], s[28:29], v[176:177] op_sel_hi:[1,0,0]
	v_max3_f32 v110, v110, v112, v108
	v_max3_f32 v108, v128, v129, v130
	v_max_f32_e32 v114, v131, v127
	v_max3_f32 v109, v149, v153, v109
	v_max3_f32 v112, v150, v151, v148
	v_max3_f32 v113, v154, v155, v152
	v_max3_f32 v108, v114, v108, v109
	v_pk_fma_f32 v[156:157], v[122:123], s[28:29], v[176:177] op_sel_hi:[1,0,0]
	v_pk_fma_f32 v[160:161], v[118:119], s[28:29], v[176:177] op_sel_hi:[1,0,0]
	v_max3_f32 v109, v112, v113, v108
	v_max3_f32 v113, v138, v139, v136
	v_pk_fma_f32 v[158:159], v[120:121], s[28:29], v[176:177] op_sel_hi:[1,0,0]
	v_pk_fma_f32 v[162:163], v[116:117], s[28:29], v[176:177] op_sel_hi:[1,0,0]
	v_max3_f32 v108, v134, v135, v132
	v_max_f32_e32 v116, v133, v137
	v_max3_f32 v113, v157, v161, v113
	v_max3_f32 v114, v158, v159, v156
	v_max3_f32 v115, v162, v163, v160
	v_max3_f32 v108, v116, v108, v113
	v_max3_f32 v112, v109, v110, v111
	v_max3_f32 v108, v114, v115, v108
	v_max_f32_e32 v112, v108, v112
	s_branch .Lattn1_need

; template <int MODE> ...
;     ...
;       if (__builtin_amdgcn_ballot_w64(need) != 0) {
; #pragma unroll
;         for (int tt = 0; tt < 2; ++tt)
; #pragma unroll
;           for (int hh = 0; hh < 2; ++hh) {
;             float mx = mxq[tt][hh];
;             mx = fmaxf(mx, __shfl_xor(mx, 16));
;             mx = fmaxf(mx, __shfl_xor(mx, 32));
;             const float d = (mx == -INFINITY) ? 0.f : (first ? mx : fmaxf(mx, 0.f));
;             const float alpha = __builtin_amdgcn_exp2f(-d);
;             lsum[tt][hh] *= alpha;
;             nbias[tt][hh] -= d;
; #pragma unroll
;             for (int dt = 0; dt < 4; ++dt)
; #pragma unroll
;               for (int j = 0; j < 4; ++j) O[tt][hh][dt][j] *= alpha;
; #pragma unroll
;             for (int kh = 0; kh < 2; ++kh)
; #pragma unroll
;               for (int t = 0; t < 2; ++t) S[kh][tt][hh][t] = S[kh][tt][hh][t] - d;
;           }
;       }
.Lattn1_need:
	s_mov_b32 s23, 0x41000000
	v_cmp_lt_f32_e32 vcc, s23, v112
	s_or_b64 s[58:59], s[42:43], vcc
	v_cndmask_b32_e64 v112, 0, 1, s[58:59]
	v_cmp_ne_u32_e32 vcc, 0, v112
	s_cbranch_vccz .LBB0_873
	v_and_b32_e32 v113, 64, v226
	v_xor_b32_e32 v112, 16, v226
	v_add_u32_e32 v113, 64, v113
	v_cmp_lt_i32_e32 vcc, v112, v113
	s_nop 1
	v_cndmask_b32_e32 v112, v226, v112, vcc
	v_lshlrev_b32_e32 v114, 2, v112
	v_xor_b32_e32 v112, 32, v226
	v_cmp_lt_i32_e32 vcc, v112, v113
	s_nop 1
	v_cndmask_b32_e32 v112, v226, v112, vcc
	v_lshlrev_b32_e32 v115, 2, v112
	ds_bpermute_b32 v112, v114, v111
	v_max_f32_e32 v111, v111, v111
	s_waitcnt lgkmcnt(0)
	v_max_f32_e32 v112, v112, v112
	v_max_f32_e32 v111, v111, v112
	ds_bpermute_b32 v112, v115, v111
	s_waitcnt lgkmcnt(0)
	v_max_f32_e32 v112, v112, v112
	v_max_f32_e32 v111, v111, v112
	v_max_f32_e32 v112, 0, v111
	v_cndmask_b32_e64 v112, v112, v111, s[42:43]
	v_cmp_neq_f32_e32 vcc, s20, v111
	s_nop 1
	v_cndmask_b32_e32 v111, 0, v112, vcc
	v_exp_f32_e64 v112, -v111
	v_sub_f32_e32 v180, v180, v111
	v_sub_f32_e32 v192, v192, v111
	v_sub_f32_e32 v193, v193, v111
	v_sub_f32_e32 v190, v190, v111
	v_sub_f32_e32 v191, v191, v111
	v_sub_f32_e32 v198, v198, v111
	v_sub_f32_e32 v199, v199, v111
	v_sub_f32_e32 v196, v196, v111
	v_sub_f32_e32 v197, v197, v111
	v_sub_f32_e32 v168, v168, v111
	v_sub_f32_e32 v169, v169, v111
	v_sub_f32_e32 v170, v170, v111
	v_sub_f32_e32 v171, v171, v111
	v_sub_f32_e32 v164, v164, v111
	v_sub_f32_e32 v165, v165, v111
	v_sub_f32_e32 v166, v166, v111
	v_sub_f32_e32 v167, v167, v111
	ds_bpermute_b32 v111, v114, v110
	v_max_f32_e32 v110, v110, v110
	v_pk_mul_f32 v[54:55], v[54:55], v[112:113] op_sel_hi:[1,0]
	v_pk_mul_f32 v[52:53], v[52:53], v[112:113] op_sel_hi:[1,0]
	v_pk_mul_f32 v[62:63], v[62:63], v[112:113] op_sel_hi:[1,0]
	s_waitcnt lgkmcnt(0)
	v_max_f32_e32 v111, v111, v111
	v_max_f32_e32 v110, v110, v111
	ds_bpermute_b32 v111, v115, v110
	v_pk_mul_f32 v[60:61], v[60:61], v[112:113] op_sel_hi:[1,0]
	v_pk_mul_f32 v[58:59], v[58:59], v[112:113] op_sel_hi:[1,0]
	v_pk_mul_f32 v[56:57], v[56:57], v[112:113] op_sel_hi:[1,0]
	v_pk_mul_f32 v[66:67], v[66:67], v[112:113] op_sel_hi:[1,0]
	s_waitcnt lgkmcnt(0)
	v_max_f32_e32 v111, v111, v111
	v_max_f32_e32 v110, v110, v111
	v_max_f32_e32 v111, 0, v110
	v_cndmask_b32_e64 v111, v111, v110, s[42:43]
	v_cmp_neq_f32_e32 vcc, s20, v110
	v_pk_mul_f32 v[64:65], v[64:65], v[112:113] op_sel_hi:[1,0]
	s_nop 0
	v_cndmask_b32_e32 v111, 0, v111, vcc
	v_exp_f32_e64 v113, -v111
	v_sub_f32_e32 v178, v178, v111
	v_sub_f32_e32 v202, v202, v111
	v_sub_f32_e32 v203, v203, v111
	v_mov_b32_e32 v110, v113
	v_pk_mul_f32 v[46:47], v[46:47], v[110:111] op_sel_hi:[1,0]
	v_pk_mul_f32 v[44:45], v[44:45], v[110:111] op_sel_hi:[1,0]
	v_pk_mul_f32 v[42:43], v[42:43], v[110:111] op_sel_hi:[1,0]
	v_pk_mul_f32 v[40:41], v[40:41], v[110:111] op_sel_hi:[1,0]
	v_pk_mul_f32 v[38:39], v[38:39], v[110:111] op_sel_hi:[1,0]
	v_pk_mul_f32 v[36:37], v[36:37], v[110:111] op_sel_hi:[1,0]
	v_pk_mul_f32 v[50:51], v[50:51], v[110:111] op_sel_hi:[1,0]
	v_pk_mul_f32 v[48:49], v[48:49], v[110:111] op_sel_hi:[1,0]
	ds_bpermute_b32 v110, v114, v109
	v_max_f32_e32 v109, v109, v109
	v_sub_f32_e32 v200, v200, v111
	v_sub_f32_e32 v201, v201, v111
	v_sub_f32_e32 v206, v206, v111
	s_waitcnt lgkmcnt(0)
	v_max_f32_e32 v110, v110, v110
	v_max_f32_e32 v109, v109, v110
	ds_bpermute_b32 v110, v115, v109
	v_sub_f32_e32 v207, v207, v111
	v_sub_f32_e32 v204, v204, v111
	v_sub_f32_e32 v205, v205, v111
	v_sub_f32_e32 v142, v142, v111
	s_waitcnt lgkmcnt(0)
	v_max_f32_e32 v110, v110, v110
	v_max_f32_e32 v109, v109, v110
	v_max_f32_e32 v110, 0, v109
	v_cndmask_b32_e64 v110, v110, v109, s[42:43]
	v_cmp_neq_f32_e32 vcc, s20, v109
	v_sub_f32_e32 v143, v143, v111
	v_sub_f32_e32 v140, v140, v111
	v_cndmask_b32_e32 v109, 0, v110, vcc
	v_exp_f32_e64 v110, -v109
	v_sub_f32_e32 v2, v2, v109
	v_sub_f32_e32 v128, v128, v109
	v_sub_f32_e32 v129, v129, v109
	v_sub_f32_e32 v130, v130, v109
	v_sub_f32_e32 v131, v131, v109
	v_sub_f32_e32 v124, v124, v109
	v_sub_f32_e32 v125, v125, v109
	v_sub_f32_e32 v126, v126, v109
	v_sub_f32_e32 v127, v127, v109
	v_sub_f32_e32 v150, v150, v109
	v_sub_f32_e32 v151, v151, v109
	v_sub_f32_e32 v148, v148, v109
	v_sub_f32_e32 v149, v149, v109
	v_sub_f32_e32 v154, v154, v109
	v_sub_f32_e32 v155, v155, v109
	v_sub_f32_e32 v152, v152, v109
	v_sub_f32_e32 v153, v153, v109
	ds_bpermute_b32 v109, v114, v108
	v_max_f32_e32 v108, v108, v108
	v_sub_f32_e32 v141, v141, v111
	v_sub_f32_e32 v146, v146, v111
	v_sub_f32_e32 v147, v147, v111
	s_waitcnt lgkmcnt(0)
	v_max_f32_e32 v109, v109, v109
	v_max_f32_e32 v108, v108, v109
	ds_bpermute_b32 v109, v115, v108
	v_sub_f32_e32 v144, v144, v111
	v_sub_f32_e32 v145, v145, v111
	v_pk_mul_f32 v[34:35], v[34:35], v[110:111] op_sel_hi:[1,0]
	v_pk_mul_f32 v[32:33], v[32:33], v[110:111] op_sel_hi:[1,0]
	s_waitcnt lgkmcnt(0)
	v_max_f32_e32 v109, v109, v109
	v_max_f32_e32 v108, v108, v109
	v_max_f32_e32 v109, 0, v108
	v_cndmask_b32_e64 v109, v109, v108, s[42:43]
	v_cmp_neq_f32_e32 vcc, s20, v108
	v_pk_mul_f32 v[30:31], v[30:31], v[110:111] op_sel_hi:[1,0]
	v_pk_mul_f32 v[28:29], v[28:29], v[110:111] op_sel_hi:[1,0]
	v_cndmask_b32_e32 v109, 0, v109, vcc
	v_pk_mul_f32 v[26:27], v[26:27], v[110:111] op_sel_hi:[1,0]
	v_pk_mul_f32 v[24:25], v[24:25], v[110:111] op_sel_hi:[1,0]
	v_pk_mul_f32 v[22:23], v[22:23], v[110:111] op_sel_hi:[1,0]
	v_pk_mul_f32 v[20:21], v[20:21], v[110:111] op_sel_hi:[1,0]
	v_exp_f32_e64 v111, -v109
	v_pk_mul_f32 v[188:189], v[188:189], v[112:113]
	v_sub_f32_e32 v176, v176, v109
	v_sub_f32_e32 v134, v134, v109
	v_mov_b32_e32 v108, v111
	v_pk_mul_f32 v[186:187], v[186:187], v[110:111]
	v_pk_mul_f32 v[18:19], v[18:19], v[108:109] op_sel_hi:[1,0]
	v_pk_mul_f32 v[16:17], v[16:17], v[108:109] op_sel_hi:[1,0]
	v_pk_mul_f32 v[14:15], v[14:15], v[108:109] op_sel_hi:[1,0]
	v_pk_mul_f32 v[12:13], v[12:13], v[108:109] op_sel_hi:[1,0]
	v_pk_mul_f32 v[10:11], v[10:11], v[108:109] op_sel_hi:[1,0]
	v_pk_mul_f32 v[8:9], v[8:9], v[108:109] op_sel_hi:[1,0]
	v_pk_mul_f32 v[6:7], v[6:7], v[108:109] op_sel_hi:[1,0]
	v_pk_mul_f32 v[4:5], v[4:5], v[108:109] op_sel_hi:[1,0]
	v_sub_f32_e32 v135, v135, v109
	v_sub_f32_e32 v132, v132, v109
	v_sub_f32_e32 v133, v133, v109
	v_sub_f32_e32 v138, v138, v109
	v_sub_f32_e32 v139, v139, v109
	v_sub_f32_e32 v136, v136, v109
	v_sub_f32_e32 v137, v137, v109
	v_sub_f32_e32 v158, v158, v109
	v_sub_f32_e32 v159, v159, v109
	v_sub_f32_e32 v156, v156, v109
	v_sub_f32_e32 v157, v157, v109
	v_sub_f32_e32 v162, v162, v109
	v_sub_f32_e32 v163, v163, v109
	v_sub_f32_e32 v160, v160, v109
	v_sub_f32_e32 v161, v161, v109

; template <int MODE> ...
;     ...
;     f32x4 S[2][2][2][2];
; #pragma unroll
;     for (int kh = 0; kh < 2; ++kh) {
;       bf16x8 kf[2][2];
; #pragma unroll
;       for (int t = 0; t < 2; ++t)
; #pragma unroll
;         for (int s2 = 0; s2 < 2; ++s2)
;           kf[t][s2] = *(const bf16x8*)&Ks[(kh * 32 + t * 16 + r) * 64 + (((s2 * 4 + g) ^ (r & 7)) * 8)];
; #pragma unroll
;       for (int tt = 0; tt < 2; ++tt)
; #pragma unroll
;         for (int hh = 0; hh < 2; ++hh) {
;           f32x4 s0 = zero4(), s1 = zero4();
;           if constexpr (MODE == 0) {
;             s0 = MFMA(kf[0][0], qf[tt][hh][0], s0);
;             s1 = MFMA(kf[1][0], qf[tt][hh][0], s1);
;             s0 = MFMA(kf[0][1], qf[tt][hh][1], s0);
;             s1 = MFMA(kf[1][1], qf[tt][hh][1], s1);
;           } else {
;             s0 = MFMA(kf[0][hh], qf[tt][hh][0], s0);
;             s1 = MFMA(kf[1][hh], qf[tt][hh][0], s1);
;           }
;           S[kh][tt][hh][0] = s0;
;           S[kh][tt][hh][1] = s1;
;         }
;     }
;     if (masked) {
; #pragma unroll
;       for (int kh = 0; kh < 2; ++kh)
; #pragma unroll
;         for (int tt = 0; tt < 2; ++tt) {
;           const int qpos = qtok0 + w * 32 + tt * 16 + r;
;           const int kp0 = kt0 + kh * 32 + g * 8;
; #pragma unroll
;           for (int t = 0; t < 2; ++t)
; #pragma unroll
;             for (int j = 0; j < 4; ++j) {
;               int d = kp0 + t * 4 + j - qpos;
;               d = d < 0 ? -d : d;
;               if (d > 128) { S[kh][tt][0][t][j] = -INFINITY; S[kh][tt][1][t][j] = -INFINITY; }
;             }
;         }
;     }
; #pragma unroll
;     for (int tt = 0; tt < 2; ++tt)
; #pragma unroll
;       for (int hh = 0; hh < 2; ++hh) {
;         const float nb = nbias[tt][hh];
; #pragma unroll
;         for (int kh = 0; kh < 2; ++kh)
; #pragma unroll
;           for (int t = 0; t < 2; ++t) S[kh][tt][hh][t] = S[kh][tt][hh][t] * c1 + nb;
;       }
;     {
;       float mxq[2][2];
;       bool need = first;
; #pragma unroll
;       for (int tt = 0; tt < 2; ++tt)
; #pragma unroll
;         for (int hh = 0; hh < 2; ++hh) {
;           const float m0 = fmaxf(fmaxf(S[0][tt][hh][0][0], S[0][tt][hh][0][1]), S[0][tt][hh][0][2]);
;           const float m1 = fmaxf(fmaxf(S[0][tt][hh][1][0], S[0][tt][hh][1][1]), S[0][tt][hh][1][2]);
;           const float m2 = fmaxf(fmaxf(S[1][tt][hh][0][0], S[1][tt][hh][0][1]), S[1][tt][hh][0][2]);
.LBB0_889:
	s_and_b64 vcc, exec, s[50:51]
	s_cbranch_vccnz .Lattn2_sorig
	s_add_i32 s52, s2, 0xffffe000
	s_and_b32 s52, s52, 0x2000
	v_lshl_add_u32 v98, s52, 1, v196
	v_add_u32_e32 v198, v98, v191
	v_add_u32_e32 v197, v98, v192
	ds_read_b128 v[90:93], v198
	ds_read_b128 v[94:97], v198 offset:2048
	ds_read_b128 v[98:101], v197
	ds_read_b128 v[102:105], v197 offset:2048
	s_waitcnt lgkmcnt(3)
	v_mfma_f32_16x16x32_bf16 v[142:145], v[90:93], v[18:21], 0
	ds_read_b128 v[174:177], v197 offset:4096
	ds_read_b128 v[178:181], v197 offset:6144
	s_andn2_b64 vcc, exec, s[50:51]
	s_waitcnt lgkmcnt(4)
	v_mfma_f32_16x16x32_bf16 v[138:141], v[94:97], v[18:21], 0
	s_waitcnt lgkmcnt(3)
	v_mfma_f32_16x16x32_bf16 v[126:129], v[98:101], v[22:25], 0
	s_waitcnt lgkmcnt(2)
	v_mfma_f32_16x16x32_bf16 v[122:125], v[102:105], v[22:25], 0
	v_mfma_f32_16x16x32_bf16 v[114:117], v[90:93], v[26:29], 0
	v_mfma_f32_16x16x32_bf16 v[106:109], v[94:97], v[26:29], 0
	v_mfma_f32_16x16x32_bf16 v[94:97], v[98:101], v[30:33], 0
	ds_read_b128 v[98:101], v198 offset:4096
	v_mfma_f32_16x16x32_bf16 v[90:93], v[102:105], v[30:33], 0
	ds_read_b128 v[102:105], v198 offset:6144
	s_waitcnt lgkmcnt(1)
	v_mfma_f32_16x16x32_bf16 v[150:153], v[98:101], v[18:21], 0
	v_pk_fma_f32 v[182:183], v[128:129], s[36:37], v[164:165] op_sel_hi:[1,0,0]
	s_waitcnt lgkmcnt(0)
	v_mfma_f32_16x16x32_bf16 v[146:149], v[102:105], v[18:21], 0
	v_pk_fma_f32 v[186:187], v[124:125], s[36:37], v[164:165] op_sel_hi:[1,0,0]
	v_mfma_f32_16x16x32_bf16 v[134:137], v[174:177], v[22:25], 0
	v_pk_fma_f32 v[188:189], v[122:123], s[36:37], v[164:165] op_sel_hi:[1,0,0]
	v_mfma_f32_16x16x32_bf16 v[130:133], v[178:181], v[22:25], 0
	v_pk_fma_f32 v[184:185], v[126:127], s[36:37], v[164:165] op_sel_hi:[1,0,0]
	v_mfma_f32_16x16x32_bf16 v[118:121], v[98:101], v[26:29], 0
	v_pk_fma_f32 v[152:153], v[152:153], s[36:37], v[162:163] op_sel_hi:[1,0,0]
	v_mfma_f32_16x16x32_bf16 v[110:113], v[102:105], v[26:29], 0
	v_pk_fma_f32 v[148:149], v[148:149], s[36:37], v[162:163] op_sel_hi:[1,0,0]
	v_mfma_f32_16x16x32_bf16 v[102:105], v[174:177], v[30:33], 0
	v_pk_fma_f32 v[174:175], v[144:145], s[36:37], v[162:163] op_sel_hi:[1,0,0]
	v_mfma_f32_16x16x32_bf16 v[98:101], v[178:181], v[30:33], 0
	v_pk_fma_f32 v[178:179], v[140:141], s[36:37], v[162:163] op_sel_hi:[1,0,0]
	v_pk_fma_f32 v[180:181], v[138:139], s[36:37], v[162:163] op_sel_hi:[1,0,0]
	v_pk_fma_f32 v[176:177], v[142:143], s[36:37], v[162:163] op_sel_hi:[1,0,0]
	v_pk_fma_f32 v[128:129], v[130:131], s[36:37], v[164:165] op_sel_hi:[1,0,0]
	v_pk_fma_f32 v[130:131], v[120:121], s[36:37], v[160:161] op_sel_hi:[1,0,0]
	v_pk_fma_f32 v[120:121], v[90:91], s[36:37], v[158:159] op_sel_hi:[1,0,0]
	v_max3_f32 v91, v180, v181, v178
	v_pk_fma_f32 v[150:151], v[150:151], s[36:37], v[162:163] op_sel_hi:[1,0,0]
	v_pk_fma_f32 v[146:147], v[146:147], s[36:37], v[162:163] op_sel_hi:[1,0,0]
	v_pk_fma_f32 v[124:125], v[134:135], s[36:37], v[164:165] op_sel_hi:[1,0,0]
	v_pk_fma_f32 v[134:135], v[112:113], s[36:37], v[160:161] op_sel_hi:[1,0,0]
	v_pk_fma_f32 v[112:113], v[94:95], s[36:37], v[158:159] op_sel_hi:[1,0,0]
	v_max3_f32 v90, v176, v177, v174
	v_max_f32_e32 v94, v175, v179
	v_max3_f32 v91, v153, v149, v91
	v_pk_fma_f32 v[122:123], v[136:137], s[36:37], v[164:165] op_sel_hi:[1,0,0]
	v_pk_fma_f32 v[126:127], v[132:133], s[36:37], v[164:165] op_sel_hi:[1,0,0]
	v_pk_fma_f32 v[132:133], v[118:119], s[36:37], v[160:161] op_sel_hi:[1,0,0]
	v_pk_fma_f32 v[118:119], v[92:93], s[36:37], v[158:159] op_sel_hi:[1,0,0]
	v_max3_f32 v92, v150, v151, v152
	v_max3_f32 v93, v146, v147, v148
	v_max3_f32 v90, v94, v90, v91
	v_max3_f32 v91, v188, v189, v186
	v_pk_fma_f32 v[108:109], v[108:109], s[36:37], v[160:161] op_sel_hi:[1,0,0]
	v_pk_fma_f32 v[106:107], v[106:107], s[36:37], v[160:161] op_sel_hi:[1,0,0]
	v_max3_f32 v93, v92, v93, v90
	v_max3_f32 v90, v184, v185, v182
	v_max_f32_e32 v95, v183, v187
	v_max3_f32 v91, v123, v127, v91
	v_pk_fma_f32 v[116:117], v[116:117], s[36:37], v[160:161] op_sel_hi:[1,0,0]
	v_pk_fma_f32 v[114:115], v[114:115], s[36:37], v[160:161] op_sel_hi:[1,0,0]
	v_max3_f32 v92, v124, v125, v122
	v_max3_f32 v94, v128, v129, v126
	v_max3_f32 v90, v95, v90, v91
	v_max3_f32 v91, v106, v107, v108
	v_pk_fma_f32 v[136:137], v[110:111], s[36:37], v[160:161] op_sel_hi:[1,0,0]
	v_pk_fma_f32 v[110:111], v[96:97], s[36:37], v[158:159] op_sel_hi:[1,0,0]
	v_max3_f32 v92, v92, v94, v90
	v_max3_f32 v90, v114, v115, v116
	v_max_f32_e32 v96, v117, v109
	v_max3_f32 v91, v131, v135, v91
	v_max3_f32 v94, v132, v133, v130
	v_max3_f32 v95, v136, v137, v134
	v_max3_f32 v90, v96, v90, v91
	v_pk_fma_f32 v[138:139], v[104:105], s[36:37], v[158:159] op_sel_hi:[1,0,0]
	v_pk_fma_f32 v[142:143], v[100:101], s[36:37], v[158:159] op_sel_hi:[1,0,0]
	v_max3_f32 v91, v94, v95, v90
	v_max3_f32 v95, v120, v121, v118
	v_pk_fma_f32 v[140:141], v[102:103], s[36:37], v[158:159] op_sel_hi:[1,0,0]
	v_pk_fma_f32 v[144:145], v[98:99], s[36:37], v[158:159] op_sel_hi:[1,0,0]
	v_max3_f32 v90, v112, v113, v110
	v_max_f32_e32 v98, v111, v119
	v_max3_f32 v95, v139, v143, v95
	v_max3_f32 v96, v140, v141, v138
	v_max3_f32 v97, v144, v145, v142
	v_max3_f32 v90, v98, v90, v95
	v_max3_f32 v94, v93, v92, v91
	v_max3_f32 v90, v96, v97, v90
	v_max_f32_e32 v94, v94, v90
	s_branch .Lattn2_need

; template <int MODE> ...
;     ...
;       if (__builtin_amdgcn_ballot_w64(need) != 0) {
; #pragma unroll
;         for (int tt = 0; tt < 2; ++tt)
; #pragma unroll
;           for (int hh = 0; hh < 2; ++hh) {
;             float mx = mxq[tt][hh];
;             mx = fmaxf(mx, __shfl_xor(mx, 16));
;             mx = fmaxf(mx, __shfl_xor(mx, 32));
;             const float d = (mx == -INFINITY) ? 0.f : (first ? mx : fmaxf(mx, 0.f));
;             const float alpha = __builtin_amdgcn_exp2f(-d);
;             lsum[tt][hh] *= alpha;
;             nbias[tt][hh] -= d;
; #pragma unroll
;             for (int dt = 0; dt < 4; ++dt)
; #pragma unroll
;               for (int j = 0; j < 4; ++j) O[tt][hh][dt][j] *= alpha;
; #pragma unroll
;             for (int kh = 0; kh < 2; ++kh)
; #pragma unroll
;               for (int t = 0; t < 2; ++t) S[kh][tt][hh][t] = S[kh][tt][hh][t] - d;
;           }
;       }
.Lattn2_need:
	s_mov_b32 s23, 0x41000000
	v_cmp_lt_f32_e32 vcc, s23, v94
	s_or_b64 s[50:51], s[42:43], vcc
	v_cndmask_b32_e64 v94, 0, 1, s[50:51]
	v_cmp_ne_u32_e32 vcc, 0, v94
	s_cbranch_vccz .LBB0_893
	v_and_b32_e32 v95, 64, v226
	v_xor_b32_e32 v94, 16, v226
	v_add_u32_e32 v95, 64, v95
	v_cmp_lt_i32_e32 vcc, v94, v95
	s_nop 1
	v_cndmask_b32_e32 v94, v226, v94, vcc
	v_lshlrev_b32_e32 v96, 2, v94
	v_xor_b32_e32 v94, 32, v226
	v_cmp_lt_i32_e32 vcc, v94, v95
	s_nop 1
	v_cndmask_b32_e32 v94, v226, v94, vcc
	v_lshlrev_b32_e32 v97, 2, v94
	ds_bpermute_b32 v94, v96, v93
	v_max_f32_e32 v93, v93, v93
	s_waitcnt lgkmcnt(0)
	v_max_f32_e32 v94, v94, v94
	v_max_f32_e32 v93, v93, v94
	ds_bpermute_b32 v94, v97, v93
	s_waitcnt lgkmcnt(0)
	v_max_f32_e32 v94, v94, v94
	v_max_f32_e32 v93, v93, v94
	v_max_f32_e32 v94, 0, v93
	v_cndmask_b32_e64 v94, v94, v93, s[42:43]
	v_cmp_neq_f32_e32 vcc, s20, v93
	s_nop 1
	v_cndmask_b32_e32 v93, 0, v94, vcc
	v_exp_f32_e64 v94, -v93
	v_sub_f32_e32 v162, v162, v93
	v_sub_f32_e32 v176, v176, v93
	v_sub_f32_e32 v177, v177, v93
	v_sub_f32_e32 v174, v174, v93
	v_sub_f32_e32 v175, v175, v93
	v_sub_f32_e32 v180, v180, v93
	v_sub_f32_e32 v181, v181, v93
	v_sub_f32_e32 v178, v178, v93
	v_sub_f32_e32 v179, v179, v93
	v_sub_f32_e32 v150, v150, v93
	v_sub_f32_e32 v151, v151, v93
	v_sub_f32_e32 v152, v152, v93
	v_sub_f32_e32 v153, v153, v93
	v_sub_f32_e32 v146, v146, v93
	v_sub_f32_e32 v147, v147, v93
	v_sub_f32_e32 v148, v148, v93
	v_sub_f32_e32 v149, v149, v93
	ds_bpermute_b32 v93, v96, v92
	v_max_f32_e32 v92, v92, v92
	v_pk_mul_f32 v[72:73], v[72:73], v[94:95] op_sel_hi:[1,0]
	v_pk_mul_f32 v[70:71], v[70:71], v[94:95] op_sel_hi:[1,0]
	v_pk_mul_f32 v[80:81], v[80:81], v[94:95] op_sel_hi:[1,0]
	s_waitcnt lgkmcnt(0)
	v_max_f32_e32 v93, v93, v93
	v_max_f32_e32 v92, v92, v93
	ds_bpermute_b32 v93, v97, v92
	v_pk_mul_f32 v[78:79], v[78:79], v[94:95] op_sel_hi:[1,0]
	v_pk_mul_f32 v[64:65], v[64:65], v[94:95] op_sel_hi:[1,0]
	v_pk_mul_f32 v[62:63], v[62:63], v[94:95] op_sel_hi:[1,0]
	v_pk_mul_f32 v[76:77], v[76:77], v[94:95] op_sel_hi:[1,0]
	s_waitcnt lgkmcnt(0)
	v_max_f32_e32 v93, v93, v93
	v_max_f32_e32 v92, v92, v93
	v_max_f32_e32 v93, 0, v92
	v_cndmask_b32_e64 v93, v93, v92, s[42:43]
	v_cmp_neq_f32_e32 vcc, s20, v92
	v_pk_mul_f32 v[74:75], v[74:75], v[94:95] op_sel_hi:[1,0]
	s_nop 0
	v_cndmask_b32_e32 v93, 0, v93, vcc
	v_exp_f32_e64 v95, -v93
	v_sub_f32_e32 v164, v164, v93
	v_sub_f32_e32 v184, v184, v93
	v_sub_f32_e32 v185, v185, v93
	v_mov_b32_e32 v92, v95
	v_pk_mul_f32 v[88:89], v[88:89], v[92:93] op_sel_hi:[1,0]
	v_pk_mul_f32 v[86:87], v[86:87], v[92:93] op_sel_hi:[1,0]
	v_pk_mul_f32 v[68:69], v[68:69], v[92:93] op_sel_hi:[1,0]
	v_pk_mul_f32 v[66:67], v[66:67], v[92:93] op_sel_hi:[1,0]
	v_pk_mul_f32 v[60:61], v[60:61], v[92:93] op_sel_hi:[1,0]
	v_pk_mul_f32 v[58:59], v[58:59], v[92:93] op_sel_hi:[1,0]
	v_pk_mul_f32 v[84:85], v[84:85], v[92:93] op_sel_hi:[1,0]
	v_pk_mul_f32 v[82:83], v[82:83], v[92:93] op_sel_hi:[1,0]
	ds_bpermute_b32 v92, v96, v91
	v_max_f32_e32 v91, v91, v91
	v_sub_f32_e32 v182, v182, v93
	v_sub_f32_e32 v183, v183, v93
	v_sub_f32_e32 v188, v188, v93
	s_waitcnt lgkmcnt(0)
	v_max_f32_e32 v92, v92, v92
	v_max_f32_e32 v91, v91, v92
	ds_bpermute_b32 v92, v97, v91
	v_sub_f32_e32 v189, v189, v93
	v_sub_f32_e32 v186, v186, v93
	v_sub_f32_e32 v187, v187, v93
	v_sub_f32_e32 v124, v124, v93
	s_waitcnt lgkmcnt(0)
	v_max_f32_e32 v92, v92, v92
	v_max_f32_e32 v91, v91, v92
	v_max_f32_e32 v92, 0, v91
	v_cndmask_b32_e64 v92, v92, v91, s[42:43]
	v_cmp_neq_f32_e32 vcc, s20, v91
	v_sub_f32_e32 v125, v125, v93
	v_sub_f32_e32 v122, v122, v93
	v_cndmask_b32_e32 v91, 0, v92, vcc
	v_exp_f32_e64 v92, -v91
	v_sub_f32_e32 v160, v160, v91
	v_sub_f32_e32 v114, v114, v91
	v_sub_f32_e32 v115, v115, v91
	v_sub_f32_e32 v116, v116, v91
	v_sub_f32_e32 v117, v117, v91
	v_sub_f32_e32 v106, v106, v91
	v_sub_f32_e32 v107, v107, v91
	v_sub_f32_e32 v108, v108, v91
	v_sub_f32_e32 v109, v109, v91
	v_sub_f32_e32 v132, v132, v91
	v_sub_f32_e32 v133, v133, v91
	v_sub_f32_e32 v130, v130, v91
	v_sub_f32_e32 v131, v131, v91
	v_sub_f32_e32 v136, v136, v91
	v_sub_f32_e32 v137, v137, v91
	v_sub_f32_e32 v134, v134, v91
	v_sub_f32_e32 v135, v135, v91
	ds_bpermute_b32 v91, v96, v90
	v_max_f32_e32 v90, v90, v90
	v_sub_f32_e32 v123, v123, v93
	v_sub_f32_e32 v128, v128, v93
	v_sub_f32_e32 v129, v129, v93
	s_waitcnt lgkmcnt(0)
	v_max_f32_e32 v91, v91, v91
	v_max_f32_e32 v90, v90, v91
	ds_bpermute_b32 v91, v97, v90
	v_sub_f32_e32 v126, v126, v93
	v_sub_f32_e32 v127, v127, v93
	v_pk_mul_f32 v[44:45], v[44:45], v[92:93] op_sel_hi:[1,0]
	v_pk_mul_f32 v[42:43], v[42:43], v[92:93] op_sel_hi:[1,0]
	s_waitcnt lgkmcnt(0)
	v_max_f32_e32 v91, v91, v91
	v_max_f32_e32 v90, v90, v91
	v_max_f32_e32 v91, 0, v90
	v_cndmask_b32_e64 v91, v91, v90, s[42:43]
	v_cmp_neq_f32_e32 vcc, s20, v90
	v_pk_mul_f32 v[36:37], v[36:37], v[92:93] op_sel_hi:[1,0]
	v_pk_mul_f32 v[34:35], v[34:35], v[92:93] op_sel_hi:[1,0]
	v_cndmask_b32_e32 v91, 0, v91, vcc
	v_pk_mul_f32 v[12:13], v[12:13], v[92:93] op_sel_hi:[1,0]
	v_pk_mul_f32 v[10:11], v[10:11], v[92:93] op_sel_hi:[1,0]
	v_pk_mul_f32 v[8:9], v[8:9], v[92:93] op_sel_hi:[1,0]
	v_pk_mul_f32 v[6:7], v[6:7], v[92:93] op_sel_hi:[1,0]
	v_exp_f32_e64 v93, -v91
	v_pk_mul_f32 v[170:171], v[170:171], v[94:95]
	v_sub_f32_e32 v158, v158, v91
	v_sub_f32_e32 v112, v112, v91
	v_mov_b32_e32 v90, v93
	v_pk_mul_f32 v[156:157], v[156:157], v[92:93]
	v_pk_mul_f32 v[48:49], v[48:49], v[90:91] op_sel_hi:[1,0]
	v_pk_mul_f32 v[46:47], v[46:47], v[90:91] op_sel_hi:[1,0]
	v_pk_mul_f32 v[40:41], v[40:41], v[90:91] op_sel_hi:[1,0]
	v_pk_mul_f32 v[38:39], v[38:39], v[90:91] op_sel_hi:[1,0]
	v_pk_mul_f32 v[16:17], v[16:17], v[90:91] op_sel_hi:[1,0]
	v_pk_mul_f32 v[14:15], v[14:15], v[90:91] op_sel_hi:[1,0]
	v_pk_mul_f32 v[4:5], v[4:5], v[90:91] op_sel_hi:[1,0]
	v_pk_mul_f32 v[2:3], v[2:3], v[90:91] op_sel_hi:[1,0]
	v_sub_f32_e32 v113, v113, v91
	v_sub_f32_e32 v110, v110, v91
	v_sub_f32_e32 v111, v111, v91
	v_sub_f32_e32 v120, v120, v91
	v_sub_f32_e32 v121, v121, v91
	v_sub_f32_e32 v118, v118, v91
	v_sub_f32_e32 v119, v119, v91
	v_sub_f32_e32 v140, v140, v91
	v_sub_f32_e32 v141, v141, v91
	v_sub_f32_e32 v138, v138, v91
	v_sub_f32_e32 v139, v139, v91
	v_sub_f32_e32 v144, v144, v91
	v_sub_f32_e32 v145, v145, v91
	v_sub_f32_e32 v142, v142, v91
	v_sub_f32_e32 v143, v143, v91
